# SSD CB^T block loop with prefetched LDS fragments; GEMM9 epilogue gate/bias vectors loaded once up front
# baseline (speedup 1.0000x reference)
; __device__ __forceinline__ unsigned cvt_pk_bf16(float lo, float hi) { unsigned r; asm volatile("s_nop 0\n\tv_cvt_pk_bf16_f32 %0, %1, %2\n\ts_nop 1" : "=v"(r) : "v"(lo), "v"(hi)); return r; }
;     __device__ __forceinline__ void operator()(f32x4 (&acc)[2][2][4][2], const Unit& u, int wr, int wc, int fr, int fq) const {
;     ...
;             for (int n = 0; n < 2; ++n) { const int col = col0 + bj * 128 + n * 16; const f32x4 gv = *(const f32x4*)(gr + col);
;                 f32x4 bv = (f32x4){0.f, 0.f, 0.f, 0.f}; if (bias) bv = *(const f32x4*)(bias + col);
; #pragma unroll
;                 for (int ai = 0; ai < 2; ++ai)
; #pragma unroll
;                     for (int m = 0; m < 4; ++m) { const size_t row = row0 + ai * 128 + m * 16;
;                         const f32x4 o = gv * (acc[ai][bj][m][n] + bv); u32x2 w; w.x = cvt_pk_bf16(o[0], o[1]); w.y = cvt_pk_bf16(o[2], o[3]);
;                         *(u32x2*)(O + row * 1024 + col) = w; } }
.LBB0_258:
	v_pk_add_f32 v[34:35], v[36:37], v[60:61]
	v_pk_add_f32 v[28:29], v[28:29], v[60:61]
	v_pk_add_f32 v[20:21], v[20:21], v[60:61]
	v_pk_add_f32 v[16:17], v[16:17], v[60:61]
	v_pk_add_f32 v[12:13], v[12:13], v[60:61]
	v_pk_add_f32 v[8:9], v[8:9], v[60:61]
	v_pk_add_f32 v[4:5], v[4:5], v[60:61]
	v_pk_add_f32 v[0:1], v[0:1], v[60:61]
	v_pk_add_f32 v[32:33], v[38:39], v[62:63]
	v_pk_mul_f32 v[34:35], v[24:25], v[34:35]
	v_pk_add_f32 v[30:31], v[30:31], v[62:63]
	v_pk_mul_f32 v[28:29], v[24:25], v[28:29]
	v_pk_add_f32 v[22:23], v[22:23], v[62:63]
	v_pk_mul_f32 v[20:21], v[24:25], v[20:21]
	v_pk_add_f32 v[18:19], v[18:19], v[62:63]
	v_pk_mul_f32 v[16:17], v[24:25], v[16:17]
	v_pk_add_f32 v[14:15], v[14:15], v[62:63]
	v_pk_mul_f32 v[12:13], v[24:25], v[12:13]
	v_pk_add_f32 v[10:11], v[10:11], v[62:63]
	v_pk_mul_f32 v[8:9], v[24:25], v[8:9]
	v_pk_add_f32 v[6:7], v[6:7], v[62:63]
	v_pk_mul_f32 v[4:5], v[24:25], v[4:5]
	v_pk_add_f32 v[2:3], v[2:3], v[62:63]
	v_pk_mul_f32 v[0:1], v[24:25], v[0:1]
	s_and_b64 vcc, exec, s[2:3]
	s_mov_b32 s51, s12
	s_mov_b32 s26, s14
	s_mov_b64 s[28:29], s[24:25]
	s_mov_b64 s[4:5], s[22:23]
	v_pk_mul_f32 v[32:33], v[26:27], v[32:33]
	v_cvt_pk_bf16_f32 v34, v34, v35
	v_pk_mul_f32 v[30:31], v[26:27], v[30:31]
	v_cvt_pk_bf16_f32 v35, v32, v33
	global_store_dwordx2 v[124:125], v[34:35], off offset:288
	v_cvt_pk_bf16_f32 v28, v28, v29
	v_cvt_pk_bf16_f32 v29, v30, v31
	global_store_dwordx2 v[120:121], v[28:29], off offset:288
	v_pk_mul_f32 v[22:23], v[26:27], v[22:23]
	v_cvt_pk_bf16_f32 v20, v20, v21
	v_pk_mul_f32 v[18:19], v[26:27], v[18:19]
	v_cvt_pk_bf16_f32 v21, v22, v23
	global_store_dwordx2 v[116:117], v[20:21], off offset:288
	v_cvt_pk_bf16_f32 v16, v16, v17
	v_cvt_pk_bf16_f32 v17, v18, v19
	global_store_dwordx2 v[112:113], v[16:17], off offset:288
	v_pk_mul_f32 v[14:15], v[26:27], v[14:15]
	v_cvt_pk_bf16_f32 v12, v12, v13
	v_pk_mul_f32 v[10:11], v[26:27], v[10:11]
	v_cvt_pk_bf16_f32 v13, v14, v15
	global_store_dwordx2 v[106:107], v[12:13], off offset:288
	v_cvt_pk_bf16_f32 v8, v8, v9
	v_cvt_pk_bf16_f32 v9, v10, v11
	global_store_dwordx2 v[104:105], v[8:9], off offset:288
	v_pk_mul_f32 v[6:7], v[26:27], v[6:7]
	v_cvt_pk_bf16_f32 v4, v4, v5
	v_pk_mul_f32 v[2:3], v[26:27], v[2:3]
	v_cvt_pk_bf16_f32 v5, v6, v7
	global_store_dwordx2 v[102:103], v[4:5], off offset:288
	v_cvt_pk_bf16_f32 v0, v0, v1
	v_cvt_pk_bf16_f32 v1, v2, v3
	s_nop 1
	global_store_dwordx2 v[100:101], v[0:1], off offset:288
	s_cbranch_vccnz .LBB0_275

; #define PG8_STAGE(bufoff, gbase, voff) do { _Pragma("unroll") for (int _i = 0; _i < 2; ++_i) \
;         __builtin_amdgcn_global_load_lds((const unsigned*)((const char*)(gbase) + (voff)[_i]), (PG8_LAS unsigned*)(lds + (bufoff) + ldsw + _i * 8192), 16, 0, 0); } while (0)
; #define PG8_LDA(dst, b, h) do { _Pragma("unroll") for (int m = 0; m < 4; ++m) _Pragma("unroll") for (int k = 0; k < 2; ++k) dst[m][k] = *(const PG8_LAS bf16x8*)(lds + PG8_SA(b, h) + aoff + m * 2048 + k * 1024); } while (0)
; #define PG8_LDB(dst, b, h) do { _Pragma("unroll") for (int n = 0; n < 2; ++n) _Pragma("unroll") for (int k = 0; k < 2; ++k) dst[n][k] = *(const PG8_LAS bf16x8*)(lds + PG8_SB(b, h) + boff + n * 2048 + k * 1024); } while (0)
; #define PG8_MMA(ai, bj, At, Bt) do { __builtin_amdgcn_s_setprio(1); _Pragma("unroll") for (int m = 0; m < 4; ++m) _Pragma("unroll") for (int n = 0; n < 2; ++n) _Pragma("unroll") for (int k = 0; k < 2; ++k) \
;         acc[ai][bj][m][n] = __builtin_amdgcn_mfma_f32_16x16x32_bf16(Bt[n][k], At[m][k], acc[ai][bj][m][n], 0, 0, 0); __builtin_amdgcn_s_setprio(0); } while (0)
; #define PG8_WAIT_L(n) asm volatile("s_waitcnt lgkmcnt(" #n ")" ::: "memory")
; #define PG8_BAR __builtin_amdgcn_s_barrier()
; #define PG8_SCHED __builtin_amdgcn_sched_barrier(0)
; template <class Epi, class Sched>
; __device__ __forceinline__ void gemm_phase(PG8_LAS unsigned char* lds, const Gemm g, const Sched& S, const Epi& E, int tid_in) {
;     ...
;             PG8_LDB(B0, 0, 0); PG8_SCHED; PG8_LDA(At, 0, 0); PG8_STAGE(PG8_SA(1, 1), a1 + hstep, voffA);
;             PG8_WAIT_L(8); PG8_BAR; PG8_WAIT_L(0); PG8_MMA(0, 0, At, B0); PG8_BAR; PG8_SCHED;
;             PG8_LDB(B1, 0, 1); PG8_STAGE(PG8_SB(0, 0), b2, voffB);
;             PG8_BAR; PG8_WAIT_L(0); PG8_MMA(0, 1, At, B1); PG8_BAR;
;             PG8_LDA(At, 0, 1); PG8_STAGE(PG8_SA(0, 0), a2, voffA);
;             PG8_BAR; PG8_WAIT_L(0); PG8_MMA(1, 0, At, B0); PG8_BAR; PG8_SCHED;
.LBB0_266:
	s_add_u32 s28, s4, 0x100
	s_addc_u32 s29, s5, 0
	s_add_i32 s58, 0, 0x10000
	v_add_u32_e32 v136, s58, v151
	ds_read_b128 v[128:131], v136
	ds_read_b128 v[132:135], v136 offset:1024
	ds_read_b128 v[144:147], v136 offset:2048
	ds_read_b128 v[154:157], v136 offset:3072
	s_cmp_eq_u32 s56, 60
	s_cselect_b32 s79, s15, s29
	s_cselect_b32 s78, s52, s28
	s_cselect_b32 s31, s13, s55
	s_cselect_b32 s30, s53, s54
	v_lshl_add_u64 v[136:137], s[4:5], 0, v[140:141]
	s_add_i32 m0, s27, 0xc000
	ds_read_b128 v[158:161], v153
	ds_read_b128 v[162:165], v153 offset:1024
	ds_read_b128 v[166:169], v153 offset:2048
	ds_read_b128 v[170:173], v153 offset:3072
	ds_read_b128 v[174:177], v153 offset:4096
	ds_read_b128 v[178:181], v153 offset:5120
	ds_read_b128 v[182:185], v153 offset:6144
	ds_read_b128 v[186:189], v153 offset:7168
	global_load_lds_dwordx4 v[136:137], off
	v_lshl_add_u64 v[136:137], s[4:5], 0, v[142:143]
	s_add_i32 m0, s27, 0xe000
	s_nop 0
	global_load_lds_dwordx4 v[136:137], off
	s_waitcnt lgkmcnt(8)
	s_barrier
	s_waitcnt lgkmcnt(0)
	s_setprio 1
	s_waitcnt lgkmcnt(0)
	v_mfma_f32_16x16x32_bf16 v[124:127], v[128:131], v[158:161], v[124:127]
	v_mfma_f32_16x16x32_bf16 v[96:99], v[144:147], v[158:161], v[96:99]
	v_mfma_f32_16x16x32_bf16 v[120:123], v[128:131], v[166:169], v[120:123]
	v_mfma_f32_16x16x32_bf16 v[88:91], v[144:147], v[166:169], v[88:91]
	v_mfma_f32_16x16x32_bf16 v[116:119], v[128:131], v[174:177], v[116:119]
	v_mfma_f32_16x16x32_bf16 v[84:87], v[144:147], v[174:177], v[84:87]
	v_mfma_f32_16x16x32_bf16 v[112:115], v[128:131], v[182:185], v[112:115]
	v_mfma_f32_16x16x32_bf16 v[80:83], v[144:147], v[182:185], v[80:83]
	v_mfma_f32_16x16x32_bf16 v[124:127], v[132:135], v[162:165], v[124:127]
	v_mfma_f32_16x16x32_bf16 v[96:99], v[154:157], v[162:165], v[96:99]
	v_mfma_f32_16x16x32_bf16 v[120:123], v[132:135], v[170:173], v[120:123]
	v_mfma_f32_16x16x32_bf16 v[88:91], v[154:157], v[170:173], v[88:91]
	v_mfma_f32_16x16x32_bf16 v[116:119], v[132:135], v[178:181], v[116:119]
	v_mfma_f32_16x16x32_bf16 v[84:87], v[154:157], v[178:181], v[84:87]
	v_mfma_f32_16x16x32_bf16 v[112:115], v[132:135], v[186:189], v[112:115]
	v_mfma_f32_16x16x32_bf16 v[80:83], v[154:157], v[186:189], v[80:83]
	s_setprio 0
	s_barrier
	s_add_i32 s59, 0, 0x14000
	v_add_u32_e32 v136, s59, v151
	s_add_i32 s4, s58, s33
	ds_read_b128 v[194:197], v136
	ds_read_b128 v[200:203], v136 offset:1024
	ds_read_b128 v[204:207], v136 offset:2048
	ds_read_b128 v[208:211], v136 offset:3072
	v_lshl_add_u64 v[136:137], s[30:31], 0, v[192:193]
	s_mov_b32 m0, s4
	v_lshl_add_u64 v[148:149], s[30:31], 0, v[138:139]
	global_load_lds_dwordx4 v[136:137], off
	s_add_i32 m0, s4, 0x2000
	s_nop 0
	global_load_lds_dwordx4 v[148:149], off
	s_barrier
	s_waitcnt lgkmcnt(0)
	s_setprio 1
	s_waitcnt lgkmcnt(0)
	v_mfma_f32_16x16x32_bf16 v[64:67], v[194:197], v[158:161], v[64:67]
	v_mfma_f32_16x16x32_bf16 v[36:39], v[204:207], v[158:161], v[36:39]
	v_mfma_f32_16x16x32_bf16 v[56:59], v[194:197], v[166:169], v[56:59]
	v_mfma_f32_16x16x32_bf16 v[28:31], v[204:207], v[166:169], v[28:31]
	v_mfma_f32_16x16x32_bf16 v[52:55], v[194:197], v[174:177], v[52:55]
	v_mfma_f32_16x16x32_bf16 v[20:23], v[204:207], v[174:177], v[20:23]
	v_mfma_f32_16x16x32_bf16 v[48:51], v[194:197], v[182:185], v[48:51]
	v_mfma_f32_16x16x32_bf16 v[16:19], v[204:207], v[182:185], v[16:19]
	v_mfma_f32_16x16x32_bf16 v[64:67], v[200:203], v[162:165], v[64:67]
	v_mfma_f32_16x16x32_bf16 v[36:39], v[208:211], v[162:165], v[36:39]
	v_mfma_f32_16x16x32_bf16 v[56:59], v[200:203], v[170:173], v[56:59]
	v_mfma_f32_16x16x32_bf16 v[28:31], v[208:211], v[170:173], v[28:31]
	v_mfma_f32_16x16x32_bf16 v[52:55], v[200:203], v[178:181], v[52:55]
	v_mfma_f32_16x16x32_bf16 v[20:23], v[208:211], v[178:181], v[20:23]
	v_mfma_f32_16x16x32_bf16 v[48:51], v[200:203], v[186:189], v[48:51]
	v_mfma_f32_16x16x32_bf16 v[16:19], v[208:211], v[186:189], v[16:19]
	s_setprio 0
	s_mov_b32 m0, s27
	v_lshl_add_u64 v[190:191], s[78:79], 0, v[192:193]
	s_barrier
	ds_read_b128 v[158:161], v153 offset:16384
	ds_read_b128 v[162:165], v153 offset:17408
	ds_read_b128 v[166:169], v153 offset:18432
	ds_read_b128 v[170:173], v153 offset:19456
	ds_read_b128 v[174:177], v153 offset:20480
	ds_read_b128 v[178:181], v153 offset:21504
	ds_read_b128 v[182:185], v153 offset:22528
	ds_read_b128 v[186:189], v153 offset:23552
	global_load_lds_dwordx4 v[190:191], off
	v_lshl_add_u64 v[212:213], s[78:79], 0, v[138:139]
	s_mov_b32 m0, s42
	s_nop 0
	global_load_lds_dwordx4 v[212:213], off
	s_barrier
	s_waitcnt lgkmcnt(0)
	s_setprio 1
	s_waitcnt lgkmcnt(0)
	v_mfma_f32_16x16x32_bf16 v[108:111], v[128:131], v[158:161], v[108:111]
	v_mfma_f32_16x16x32_bf16 v[76:79], v[144:147], v[158:161], v[76:79]
	v_mfma_f32_16x16x32_bf16 v[104:107], v[128:131], v[166:169], v[104:107]
	v_mfma_f32_16x16x32_bf16 v[72:75], v[144:147], v[166:169], v[72:75]
	v_mfma_f32_16x16x32_bf16 v[100:103], v[128:131], v[174:177], v[100:103]
	v_mfma_f32_16x16x32_bf16 v[68:71], v[144:147], v[174:177], v[68:71]
	v_mfma_f32_16x16x32_bf16 v[92:95], v[128:131], v[182:185], v[92:95]
	v_mfma_f32_16x16x32_bf16 v[60:63], v[144:147], v[182:185], v[60:63]
	v_mfma_f32_16x16x32_bf16 v[108:111], v[132:135], v[162:165], v[108:111]
	v_mfma_f32_16x16x32_bf16 v[76:79], v[154:157], v[162:165], v[76:79]
	v_mfma_f32_16x16x32_bf16 v[104:107], v[132:135], v[170:173], v[104:107]
	v_mfma_f32_16x16x32_bf16 v[72:75], v[154:157], v[170:173], v[72:75]
	v_mfma_f32_16x16x32_bf16 v[100:103], v[132:135], v[178:181], v[100:103]
	v_mfma_f32_16x16x32_bf16 v[68:71], v[154:157], v[178:181], v[68:71]
	v_mfma_f32_16x16x32_bf16 v[92:95], v[132:135], v[186:189], v[92:95]
	v_mfma_f32_16x16x32_bf16 v[60:63], v[154:157], v[186:189], v[60:63]
	s_setprio 0
	s_barrier
; #define PG8_STAGE(bufoff, gbase, voff) do { _Pragma("unroll") for (int _i = 0; _i < 2; ++_i) \
;         __builtin_amdgcn_global_load_lds((const unsigned*)((const char*)(gbase) + (voff)[_i]), (PG8_LAS unsigned*)(lds + (bufoff) + ldsw + _i * 8192), 16, 0, 0); } while (0)
; #define PG8_LDA(dst, b, h) do { _Pragma("unroll") for (int m = 0; m < 4; ++m) _Pragma("unroll") for (int k = 0; k < 2; ++k) dst[m][k] = *(const PG8_LAS bf16x8*)(lds + PG8_SA(b, h) + aoff + m * 2048 + k * 1024); } while (0)
; #define PG8_LDB(dst, b, h) do { _Pragma("unroll") for (int n = 0; n < 2; ++n) _Pragma("unroll") for (int k = 0; k < 2; ++k) dst[n][k] = *(const PG8_LAS bf16x8*)(lds + PG8_SB(b, h) + boff + n * 2048 + k * 1024); } while (0)
; #define PG8_MMA(ai, bj, At, Bt) do { __builtin_amdgcn_s_setprio(1); _Pragma("unroll") for (int m = 0; m < 4; ++m) _Pragma("unroll") for (int n = 0; n < 2; ++n) _Pragma("unroll") for (int k = 0; k < 2; ++k) \
;         acc[ai][bj][m][n] = __builtin_amdgcn_mfma_f32_16x16x32_bf16(Bt[n][k], At[m][k], acc[ai][bj][m][n], 0, 0, 0); __builtin_amdgcn_s_setprio(0); } while (0)
; #define PG8_WAIT_V(n) asm volatile("s_waitcnt vmcnt(" #n ")" ::: "memory")
; #define PG8_WAIT_L(n) asm volatile("s_waitcnt lgkmcnt(" #n ")" ::: "memory")
; #define PG8_BAR __builtin_amdgcn_s_barrier()
; #define PG8_SCHED __builtin_amdgcn_sched_barrier(0)
; template <class Epi, class Sched>
; __device__ __forceinline__ void gemm_phase(PG8_LAS unsigned char* lds, const Gemm g, const Sched& S, const Epi& E, int tid_in) {
;     ...
;             PG8_STAGE(PG8_SB(0, 1), b2 + hstep, voffB);
;             PG8_WAIT_V(6); PG8_BAR; PG8_MMA(1, 1, At, B1); PG8_BAR;
;             PG8_LDB(B0, 1, 0); PG8_SCHED; PG8_LDA(At, 1, 0); PG8_STAGE(PG8_SA(0, 1), a2 + hstep, voffA);
;             PG8_WAIT_L(8); PG8_BAR; PG8_WAIT_L(0); PG8_MMA(0, 0, At, B0); PG8_BAR; PG8_SCHED;
;             PG8_LDB(B1, 1, 1); PG8_STAGE(PG8_SB(1, 0), b3, voffB);
;             PG8_BAR; PG8_WAIT_L(0); PG8_MMA(0, 1, At, B1); PG8_BAR;
;             PG8_LDA(At, 1, 1); PG8_STAGE(PG8_SA(1, 0), a3, voffA);
	s_add_u32 s4, s30, 0x100000
	s_addc_u32 s5, s31, 0
	s_add_i32 s58, s59, s33
	v_lshl_add_u64 v[128:129], s[4:5], 0, v[192:193]
	s_mov_b32 m0, s58
	s_nop 0
	global_load_lds_dwordx4 v[128:129], off
	v_lshl_add_u64 v[128:129], s[4:5], 0, v[138:139]
	s_add_i32 m0, s58, 0x2000
	s_nop 0
	global_load_lds_dwordx4 v[128:129], off
	s_waitcnt vmcnt(6)
	s_barrier
	s_setprio 1
	v_mfma_f32_16x16x32_bf16 v[44:47], v[194:197], v[158:161], v[44:47]
	v_mfma_f32_16x16x32_bf16 v[12:15], v[204:207], v[158:161], v[12:15]
	v_mfma_f32_16x16x32_bf16 v[40:43], v[194:197], v[166:169], v[40:43]
	v_mfma_f32_16x16x32_bf16 v[8:11], v[204:207], v[166:169], v[8:11]
	v_mfma_f32_16x16x32_bf16 v[32:35], v[194:197], v[174:177], v[32:35]
	v_mfma_f32_16x16x32_bf16 v[4:7], v[204:207], v[174:177], v[4:7]
	v_mfma_f32_16x16x32_bf16 v[24:27], v[194:197], v[182:185], v[24:27]
	v_mfma_f32_16x16x32_bf16 v[0:3], v[204:207], v[182:185], v[0:3]
	v_mfma_f32_16x16x32_bf16 v[44:47], v[200:203], v[162:165], v[44:47]
	v_mfma_f32_16x16x32_bf16 v[12:15], v[208:211], v[162:165], v[12:15]
	v_mfma_f32_16x16x32_bf16 v[40:43], v[200:203], v[170:173], v[40:43]
	v_mfma_f32_16x16x32_bf16 v[8:11], v[208:211], v[170:173], v[8:11]
	v_mfma_f32_16x16x32_bf16 v[32:35], v[200:203], v[178:181], v[32:35]
	v_mfma_f32_16x16x32_bf16 v[4:7], v[208:211], v[178:181], v[4:7]
	v_mfma_f32_16x16x32_bf16 v[24:27], v[200:203], v[186:189], v[24:27]
	v_mfma_f32_16x16x32_bf16 v[0:3], v[208:211], v[186:189], v[0:3]
	s_setprio 0
	s_add_i32 s58, 0, 0x18000
	v_add_u32_e32 v154, s58, v151
	s_barrier
	ds_read_b128 v[128:131], v154
	ds_read_b128 v[132:135], v154 offset:1024
	ds_read_b128 v[144:147], v154 offset:2048
	ds_read_b128 v[154:157], v154 offset:3072
	s_add_u32 s4, s78, 0x100000
	s_addc_u32 s5, s79, 0
	s_mov_b32 m0, s43
	v_lshl_add_u64 v[194:195], s[4:5], 0, v[192:193]
	ds_read_b128 v[158:161], v153 offset:32768
	ds_read_b128 v[162:165], v153 offset:33792
	ds_read_b128 v[166:169], v153 offset:34816
	ds_read_b128 v[170:173], v153 offset:35840
	ds_read_b128 v[174:177], v153 offset:36864
	ds_read_b128 v[178:181], v153 offset:37888
	ds_read_b128 v[182:185], v153 offset:38912
	ds_read_b128 v[186:189], v153 offset:39936
	global_load_lds_dwordx4 v[194:195], off
	v_lshl_add_u64 v[194:195], s[4:5], 0, v[138:139]
	s_mov_b32 m0, s44
	s_nop 0
	global_load_lds_dwordx4 v[194:195], off
	s_waitcnt lgkmcnt(8)
	s_barrier
	s_waitcnt lgkmcnt(0)
	s_setprio 1
	s_waitcnt lgkmcnt(0)
	v_mfma_f32_16x16x32_bf16 v[124:127], v[128:131], v[158:161], v[124:127]
	v_mfma_f32_16x16x32_bf16 v[96:99], v[144:147], v[158:161], v[96:99]
	v_mfma_f32_16x16x32_bf16 v[120:123], v[128:131], v[166:169], v[120:123]
	v_mfma_f32_16x16x32_bf16 v[88:91], v[144:147], v[166:169], v[88:91]
	v_mfma_f32_16x16x32_bf16 v[116:119], v[128:131], v[174:177], v[116:119]
	v_mfma_f32_16x16x32_bf16 v[84:87], v[144:147], v[174:177], v[84:87]
	v_mfma_f32_16x16x32_bf16 v[112:115], v[128:131], v[182:185], v[112:115]
	v_mfma_f32_16x16x32_bf16 v[80:83], v[144:147], v[182:185], v[80:83]
	v_mfma_f32_16x16x32_bf16 v[124:127], v[132:135], v[162:165], v[124:127]
	v_mfma_f32_16x16x32_bf16 v[96:99], v[154:157], v[162:165], v[96:99]
	v_mfma_f32_16x16x32_bf16 v[120:123], v[132:135], v[170:173], v[120:123]
	v_mfma_f32_16x16x32_bf16 v[88:91], v[154:157], v[170:173], v[88:91]
	v_mfma_f32_16x16x32_bf16 v[116:119], v[132:135], v[178:181], v[116:119]
	v_mfma_f32_16x16x32_bf16 v[84:87], v[154:157], v[178:181], v[84:87]
	v_mfma_f32_16x16x32_bf16 v[112:115], v[132:135], v[186:189], v[112:115]
	v_mfma_f32_16x16x32_bf16 v[80:83], v[154:157], v[186:189], v[80:83]
	s_setprio 0
	s_barrier
	s_add_i32 s59, 0, 0x1c000
	s_add_i32 s4, s58, s33
	v_add_u32_e32 v199, s59, v151
	v_lshl_add_u64 v[136:137], v[136:137], 0, s[74:75]
	s_mov_b32 m0, s4
	ds_read_b128 v[194:197], v199
	ds_read_b128 v[200:203], v199 offset:1024
	ds_read_b128 v[204:207], v199 offset:2048
	ds_read_b128 v[208:211], v199 offset:3072
	global_load_lds_dwordx4 v[136:137], off
	v_lshl_add_u64 v[136:137], v[148:149], 0, s[74:75]
	s_add_i32 m0, s4, 0x2000
	s_nop 0
	global_load_lds_dwordx4 v[136:137], off
	s_barrier
	s_waitcnt lgkmcnt(0)
	s_setprio 1
	s_waitcnt lgkmcnt(0)
	v_mfma_f32_16x16x32_bf16 v[64:67], v[194:197], v[158:161], v[64:67]
	v_mfma_f32_16x16x32_bf16 v[36:39], v[204:207], v[158:161], v[36:39]
	v_mfma_f32_16x16x32_bf16 v[56:59], v[194:197], v[166:169], v[56:59]
	v_mfma_f32_16x16x32_bf16 v[28:31], v[204:207], v[166:169], v[28:31]
	v_mfma_f32_16x16x32_bf16 v[52:55], v[194:197], v[174:177], v[52:55]
	v_mfma_f32_16x16x32_bf16 v[20:23], v[204:207], v[174:177], v[20:23]
	v_mfma_f32_16x16x32_bf16 v[48:51], v[194:197], v[182:185], v[48:51]
	v_mfma_f32_16x16x32_bf16 v[16:19], v[204:207], v[182:185], v[16:19]
	v_mfma_f32_16x16x32_bf16 v[64:67], v[200:203], v[162:165], v[64:67]
	v_mfma_f32_16x16x32_bf16 v[36:39], v[208:211], v[162:165], v[36:39]
	v_mfma_f32_16x16x32_bf16 v[56:59], v[200:203], v[170:173], v[56:59]
	v_mfma_f32_16x16x32_bf16 v[28:31], v[208:211], v[170:173], v[28:31]
	v_mfma_f32_16x16x32_bf16 v[52:55], v[200:203], v[178:181], v[52:55]
	v_mfma_f32_16x16x32_bf16 v[20:23], v[208:211], v[178:181], v[20:23]
	v_mfma_f32_16x16x32_bf16 v[48:51], v[200:203], v[186:189], v[48:51]
	v_mfma_f32_16x16x32_bf16 v[16:19], v[208:211], v[186:189], v[16:19]
	s_setprio 0
	s_mov_b32 m0, s48
	v_lshl_add_u64 v[136:137], v[190:191], 0, s[74:75]
	s_barrier
	ds_read_b128 v[158:161], v153 offset:49152
	ds_read_b128 v[162:165], v153 offset:50176
	ds_read_b128 v[166:169], v153 offset:51200
	ds_read_b128 v[170:173], v153 offset:52224
	ds_read_b128 v[174:177], v153 offset:53248
	ds_read_b128 v[178:181], v153 offset:54272
	ds_read_b128 v[182:185], v153 offset:55296
	ds_read_b128 v[186:189], v153 offset:56320
	global_load_lds_dwordx4 v[136:137], off
	v_lshl_add_u64 v[136:137], v[212:213], 0, s[74:75]
	s_mov_b32 m0, s49
	s_nop 0
	global_load_lds_dwordx4 v[136:137], off
	s_barrier
; __device__ __forceinline__ unsigned cvt_pk_bf16(float lo, float hi) { unsigned r; asm volatile("s_nop 0\n\tv_cvt_pk_bf16_f32 %0, %1, %2\n\ts_nop 1" : "=v"(r) : "v"(lo), "v"(hi)); return r; }
; #define PG8_STAGE(bufoff, gbase, voff) do { _Pragma("unroll") for (int _i = 0; _i < 2; ++_i) \
;         __builtin_amdgcn_global_load_lds((const unsigned*)((const char*)(gbase) + (voff)[_i]), (PG8_LAS unsigned*)(lds + (bufoff) + ldsw + _i * 8192), 16, 0, 0); } while (0)
; #define PG8_MMA(ai, bj, At, Bt) do { __builtin_amdgcn_s_setprio(1); _Pragma("unroll") for (int m = 0; m < 4; ++m) _Pragma("unroll") for (int n = 0; n < 2; ++n) _Pragma("unroll") for (int k = 0; k < 2; ++k) \
;         acc[ai][bj][m][n] = __builtin_amdgcn_mfma_f32_16x16x32_bf16(Bt[n][k], At[m][k], acc[ai][bj][m][n], 0, 0, 0); __builtin_amdgcn_s_setprio(0); } while (0)
; #define PG8_WAIT_V(n) asm volatile("s_waitcnt vmcnt(" #n ")" ::: "memory")
; #define PG8_WAIT_L(n) asm volatile("s_waitcnt lgkmcnt(" #n ")" ::: "memory")
; template <class Epi, class Sched>
; __device__ __forceinline__ void gemm_phase(PG8_LAS unsigned char* lds, const Gemm g, const Sched& S, const Epi& E, int tid_in) {
;     ...
;             PG8_BAR; PG8_WAIT_L(0); PG8_MMA(1, 0, At, B0); PG8_BAR; PG8_SCHED;
;             PG8_STAGE(PG8_SB(1, 1), b3 + hstep, voffB);
;             PG8_WAIT_V(6); PG8_BAR; PG8_MMA(1, 1, At, B1); PG8_BAR;
;     __device__ __forceinline__ void operator()(f32x4 (&acc)[2][2][4][2], const Unit& u, int wr, int wc, int fr, int fq) const {
;         const int row0 = u.pm * 256 + wr * 64 + fr, col0 = u.pn * 256 + wc * 32 + 4 * fq;
;         const float* gr = gate + (size_t)(bbase + (u.pm * 256) / SEQ) * MODW;
; #pragma unroll
;         for (int bj = 0; bj < 2; ++bj)
; #pragma unroll
;             for (int n = 0; n < 2; ++n) { const int col = col0 + bj * 128 + n * 16; const f32x4 gv = *(const f32x4*)(gr + col);
;                 f32x4 bv = (f32x4){0.f, 0.f, 0.f, 0.f}; if (bias) bv = *(const f32x4*)(bias + col);
; #pragma unroll
;                 for (int ai = 0; ai < 2; ++ai)
; #pragma unroll
;                     for (int m = 0; m < 4; ++m) { const size_t row = row0 + ai * 128 + m * 16;
;                         const f32x4 o = gv * (acc[ai][bj][m][n] + bv); u32x2 w; w.x = cvt_pk_bf16(o[0], o[1]); w.y = cvt_pk_bf16(o[2], o[3]);
;                         *(u32x2*)(O + row * 1024 + col) = w; } }
	s_waitcnt lgkmcnt(0)
	s_setprio 1
	s_waitcnt lgkmcnt(0)
	v_mfma_f32_16x16x32_bf16 v[108:111], v[128:131], v[158:161], v[108:111]
	v_mfma_f32_16x16x32_bf16 v[76:79], v[144:147], v[158:161], v[76:79]
	v_mfma_f32_16x16x32_bf16 v[104:107], v[128:131], v[166:169], v[104:107]
	v_mfma_f32_16x16x32_bf16 v[72:75], v[144:147], v[166:169], v[72:75]
	v_mfma_f32_16x16x32_bf16 v[100:103], v[128:131], v[174:177], v[100:103]
	v_mfma_f32_16x16x32_bf16 v[68:71], v[144:147], v[174:177], v[68:71]
	v_mfma_f32_16x16x32_bf16 v[92:95], v[128:131], v[182:185], v[92:95]
	v_mfma_f32_16x16x32_bf16 v[60:63], v[144:147], v[182:185], v[60:63]
	v_mfma_f32_16x16x32_bf16 v[108:111], v[132:135], v[162:165], v[108:111]
	v_mfma_f32_16x16x32_bf16 v[76:79], v[154:157], v[162:165], v[76:79]
	v_mfma_f32_16x16x32_bf16 v[104:107], v[132:135], v[170:173], v[104:107]
	v_mfma_f32_16x16x32_bf16 v[72:75], v[154:157], v[170:173], v[72:75]
	v_mfma_f32_16x16x32_bf16 v[100:103], v[132:135], v[178:181], v[100:103]
	v_mfma_f32_16x16x32_bf16 v[68:71], v[154:157], v[178:181], v[68:71]
	v_mfma_f32_16x16x32_bf16 v[92:95], v[132:135], v[186:189], v[92:95]
	v_mfma_f32_16x16x32_bf16 v[60:63], v[154:157], v[186:189], v[60:63]
	s_setprio 0
	s_barrier
	s_add_u32 s4, s30, 0x100080
	s_addc_u32 s5, s31, 0
	s_add_i32 s30, s59, s33
	v_lshl_add_u64 v[128:129], s[4:5], 0, v[192:193]
	s_mov_b32 m0, s30
	s_nop 0
	global_load_lds_dwordx4 v[128:129], off
	v_lshl_add_u64 v[128:129], s[4:5], 0, v[138:139]
	s_add_i32 m0, s30, 0x2000
	s_nop 0
	global_load_lds_dwordx4 v[128:129], off
	s_waitcnt vmcnt(6)
	s_barrier
	s_setprio 1
	v_mfma_f32_16x16x32_bf16 v[44:47], v[194:197], v[158:161], v[44:47]
	v_mfma_f32_16x16x32_bf16 v[12:15], v[204:207], v[158:161], v[12:15]
	v_mfma_f32_16x16x32_bf16 v[40:43], v[194:197], v[166:169], v[40:43]
	v_mfma_f32_16x16x32_bf16 v[8:11], v[204:207], v[166:169], v[8:11]
	v_mfma_f32_16x16x32_bf16 v[32:35], v[194:197], v[174:177], v[32:35]
	v_mfma_f32_16x16x32_bf16 v[4:7], v[204:207], v[174:177], v[4:7]
	v_mfma_f32_16x16x32_bf16 v[24:27], v[194:197], v[182:185], v[24:27]
	v_mfma_f32_16x16x32_bf16 v[0:3], v[204:207], v[182:185], v[0:3]
	v_mfma_f32_16x16x32_bf16 v[44:47], v[200:203], v[162:165], v[44:47]
	v_mfma_f32_16x16x32_bf16 v[12:15], v[208:211], v[162:165], v[12:15]
	v_mfma_f32_16x16x32_bf16 v[40:43], v[200:203], v[170:173], v[40:43]
	v_mfma_f32_16x16x32_bf16 v[8:11], v[208:211], v[170:173], v[8:11]
	v_mfma_f32_16x16x32_bf16 v[32:35], v[200:203], v[178:181], v[32:35]
	v_mfma_f32_16x16x32_bf16 v[4:7], v[208:211], v[178:181], v[4:7]
	v_mfma_f32_16x16x32_bf16 v[24:27], v[200:203], v[186:189], v[24:27]
	v_mfma_f32_16x16x32_bf16 v[0:3], v[208:211], v[186:189], v[0:3]
	s_setprio 0
	s_add_i32 s56, s56, 2
	s_add_u32 s54, s54, 0x100
	s_addc_u32 s55, s55, 0
	s_cmp_gt_u32 s56, 61
	s_mov_b64 s[4:5], s[28:29]
	s_barrier
	s_cbranch_scc0 .LBB0_266
	s_ashr_i32 s4, s26, 31
	s_lshr_b32 s4, s4, 29
	s_add_i32 s4, s26, s4
	s_ashr_i32 s4, s4, 3
	s_add_i32 s4, s4, s76
	s_mul_hi_i32 s5, s4, 0x6000
	s_mulk_i32 s4, 0x6000
	v_lshl_or_b32 v148, s51, 8, v152
	s_add_u32 s4, s45, s4
	s_addc_u32 s5, s46, s5
	v_ashrrev_i32_e32 v149, 31, v148
	v_lshl_add_u64 v[146:147], v[148:149], 2, s[4:5]
	global_load_dwordx4 v[130:133], v[146:147], off
	global_load_dwordx4 v[158:161], v[146:147], off offset:64
	global_load_dwordx4 v[162:165], v[146:147], off offset:512
	global_load_dwordx4 v[166:169], v[146:147], off offset:576
	v_cndmask_b32_e64 v129, 0, 1, s[10:11]
	v_mov_b32_e32 v128, 0
	v_cmp_ne_u32_e64 s[4:5], 1, v129
	s_andn2_b64 vcc, exec, s[10:11]
	v_lshl_add_u64 v[144:145], v[148:149], 2, s[8:9]
	v_mov_b32_e32 v134, 0
	v_mov_b32_e32 v135, 0
	v_mov_b32_e32 v136, 0
	v_mov_b32_e32 v137, 0
	s_cbranch_vccnz .LBB0_269
	global_load_dwordx4 v[134:137], v[144:145], off
	global_load_dwordx4 v[170:173], v[144:145], off offset:64
	global_load_dwordx4 v[174:177], v[144:145], off offset:512
	global_load_dwordx4 v[178:181], v[144:145], off offset:576
.LBB0_269:
	v_lshl_add_u32 v154, s26, 8, v150
	s_waitcnt vmcnt(0)
	v_pk_add_f32 v[124:125], v[124:125], v[134:135]
	v_ashrrev_i32_e32 v155, 31, v154
	v_pk_add_f32 v[126:127], v[126:127], v[136:137]
	v_pk_mul_f32 v[124:125], v[130:131], v[124:125]
	v_pk_mul_f32 v[126:127], v[132:133], v[126:127]
	s_nop 0
	v_cvt_pk_bf16_f32 v156, v124, v125
	v_lshlrev_b64 v[124:125], 11, v[154:155]
	s_nop 0
	v_cvt_pk_bf16_f32 v157, v126, v127
	v_lshl_add_u64 v[124:125], s[0:1], 0, v[124:125]
	v_lshlrev_b64 v[126:127], 1, v[148:149]
	v_or_b32_e32 v148, 16, v154
	v_pk_add_f32 v[120:121], v[120:121], v[134:135]
	v_lshl_add_u64 v[124:125], v[124:125], 0, v[126:127]
	v_ashrrev_i32_e32 v149, 31, v148
	v_pk_add_f32 v[122:123], v[122:123], v[136:137]
	v_pk_mul_f32 v[120:121], v[130:131], v[120:121]
	global_store_dwordx2 v[124:125], v[156:157], off
	v_pk_mul_f32 v[122:123], v[132:133], v[122:123]
	v_cvt_pk_bf16_f32 v156, v120, v121
	v_lshlrev_b64 v[120:121], 11, v[148:149]
	v_cvt_pk_bf16_f32 v157, v122, v123
	v_lshl_add_u64 v[120:121], s[0:1], 0, v[120:121]
	v_or_b32_e32 v122, 32, v154
	v_pk_add_f32 v[116:117], v[116:117], v[134:135]
	v_lshl_add_u64 v[120:121], v[120:121], 0, v[126:127]
	v_ashrrev_i32_e32 v123, 31, v122
	v_pk_add_f32 v[118:119], v[118:119], v[136:137]
	v_pk_mul_f32 v[116:117], v[130:131], v[116:117]
	global_store_dwordx2 v[120:121], v[156:157], off
	v_pk_mul_f32 v[118:119], v[132:133], v[118:119]
	v_cvt_pk_bf16_f32 v148, v116, v117
	v_lshlrev_b64 v[116:117], 11, v[122:123]
	v_cvt_pk_bf16_f32 v149, v118, v119
	v_lshl_add_u64 v[116:117], s[0:1], 0, v[116:117]
	v_or_b32_e32 v118, 48, v154
	v_pk_add_f32 v[112:113], v[112:113], v[134:135]
	v_lshl_add_u64 v[116:117], v[116:117], 0, v[126:127]
; __device__ __forceinline__ unsigned cvt_pk_bf16(float lo, float hi) { unsigned r; asm volatile("s_nop 0\n\tv_cvt_pk_bf16_f32 %0, %1, %2\n\ts_nop 1" : "=v"(r) : "v"(lo), "v"(hi)); return r; }
;     __device__ __forceinline__ void operator()(f32x4 (&acc)[2][2][4][2], const Unit& u, int wr, int wc, int fr, int fq) const {
;     ...
;         for (int bj = 0; bj < 2; ++bj)
; #pragma unroll
;             for (int n = 0; n < 2; ++n) { const int col = col0 + bj * 128 + n * 16; const f32x4 gv = *(const f32x4*)(gr + col);
;                 f32x4 bv = (f32x4){0.f, 0.f, 0.f, 0.f}; if (bias) bv = *(const f32x4*)(bias + col);
; #pragma unroll
;                 for (int ai = 0; ai < 2; ++ai)
; #pragma unroll
;                     for (int m = 0; m < 4; ++m) { const size_t row = row0 + ai * 128 + m * 16;
;                         const f32x4 o = gv * (acc[ai][bj][m][n] + bv); u32x2 w; w.x = cvt_pk_bf16(o[0], o[1]); w.y = cvt_pk_bf16(o[2], o[3]);
;                         *(u32x2*)(O + row * 1024 + col) = w; } }
	v_ashrrev_i32_e32 v119, 31, v118
	v_pk_mul_f32 v[112:113], v[130:131], v[112:113]
	global_store_dwordx2 v[116:117], v[148:149], off
	v_cvt_pk_bf16_f32 v122, v112, v113
	v_lshlrev_b64 v[112:113], 11, v[118:119]
	v_lshl_add_u64 v[112:113], s[0:1], 0, v[112:113]
	v_pk_add_f32 v[110:111], v[110:111], v[136:137]
	v_pk_add_f32 v[108:109], v[108:109], v[134:135]
	v_pk_add_f32 v[114:115], v[114:115], v[136:137]
	v_lshl_add_u64 v[112:113], v[112:113], 0, v[126:127]
	v_pk_mul_f32 v[110:111], v[132:133], v[110:111]
	v_pk_mul_f32 v[108:109], v[130:131], v[108:109]
	v_pk_mul_f32 v[114:115], v[132:133], v[114:115]
	v_pk_add_f32 v[106:107], v[106:107], v[136:137]
	v_cvt_pk_bf16_f32 v123, v114, v115
	global_store_dwordx2 v[112:113], v[122:123], off
	v_cvt_pk_bf16_f32 v108, v108, v109
	v_cvt_pk_bf16_f32 v109, v110, v111
	v_add_co_u32_e32 v110, vcc, s63, v124
	v_pk_add_f32 v[104:105], v[104:105], v[134:135]
	s_nop 0
	v_addc_co_u32_e32 v111, vcc, 0, v125, vcc
	v_pk_mul_f32 v[106:107], v[132:133], v[106:107]
	v_pk_mul_f32 v[104:105], v[130:131], v[104:105]
	global_store_dwordx2 v[110:111], v[108:109], off
	v_cvt_pk_bf16_f32 v104, v104, v105
	v_cvt_pk_bf16_f32 v105, v106, v107
	v_add_co_u32_e32 v106, vcc, s66, v124
	v_pk_add_f32 v[102:103], v[102:103], v[136:137]
	v_pk_add_f32 v[100:101], v[100:101], v[134:135]
	v_addc_co_u32_e32 v107, vcc, 0, v125, vcc
	v_pk_mul_f32 v[102:103], v[132:133], v[102:103]
	v_pk_mul_f32 v[100:101], v[130:131], v[100:101]
	s_mov_b32 s55, 0x50000
	global_store_dwordx2 v[106:107], v[104:105], off
	v_cvt_pk_bf16_f32 v100, v100, v101
	v_cvt_pk_bf16_f32 v101, v102, v103
	v_add_co_u32_e32 v102, vcc, s55, v124
	v_pk_add_f32 v[94:95], v[94:95], v[136:137]
	v_pk_add_f32 v[92:93], v[92:93], v[134:135]
	v_addc_co_u32_e32 v103, vcc, 0, v125, vcc
	v_pk_mul_f32 v[94:95], v[132:133], v[94:95]
	v_pk_mul_f32 v[92:93], v[130:131], v[92:93]
	global_store_dwordx2 v[102:103], v[100:101], off
	v_cvt_pk_bf16_f32 v92, v92, v93
	v_cvt_pk_bf16_f32 v93, v94, v95
	v_add_co_u32_e32 v94, vcc, 0x58000, v124
	v_mov_b32_e32 v129, 0
	s_nop 0
	v_addc_co_u32_e32 v95, vcc, 0, v125, vcc
	global_store_dwordx2 v[94:95], v[92:93], off
	s_nop 0
	v_mov_b32_e32 v92, v158
	v_mov_b32_e32 v93, v159
	v_mov_b32_e32 v94, v160
	v_mov_b32_e32 v95, v161
	s_and_b64 vcc, exec, s[4:5]
	v_mov_b32_e32 v130, 0
	v_mov_b32_e32 v131, 0
	s_mov_b32 s56, 0x800000
	s_mov_b32 s58, 0x3f317217
	s_mov_b32 s59, 0x7f800000
	s_movk_i32 s78, 0x2a00
	v_readlane_b32 s79, v255, 35
	s_cbranch_vccnz .LBB0_271
	v_mov_b32_e32 v128, v170
	v_mov_b32_e32 v129, v171
	v_mov_b32_e32 v130, v172
	v_mov_b32_e32 v131, v173
.LBB0_271:
	s_mov_b64 s[28:29], 0x40000
	v_lshl_add_u64 v[106:107], v[124:125], 0, s[28:29]
	s_mov_b64 s[28:29], 0x50000
	v_lshl_add_u64 v[102:103], v[124:125], 0, s[28:29]
	s_mov_b64 s[28:29], 0x58000
	v_pk_add_f32 v[96:97], v[96:97], v[128:129]
	v_pk_add_f32 v[88:89], v[88:89], v[128:129]
	v_pk_add_f32 v[84:85], v[84:85], v[128:129]
	v_pk_add_f32 v[80:81], v[80:81], v[128:129]
	v_pk_add_f32 v[76:77], v[76:77], v[128:129]
	v_pk_add_f32 v[72:73], v[72:73], v[128:129]
	v_pk_add_f32 v[68:69], v[68:69], v[128:129]
	v_pk_add_f32 v[60:61], v[60:61], v[128:129]
	v_lshl_add_u64 v[104:105], v[124:125], 0, s[64:65]
	v_lshl_add_u64 v[100:101], v[124:125], 0, s[28:29]
	v_pk_add_f32 v[98:99], v[98:99], v[130:131]
	v_pk_mul_f32 v[96:97], v[92:93], v[96:97]
	v_pk_add_f32 v[90:91], v[90:91], v[130:131]
	v_pk_mul_f32 v[88:89], v[92:93], v[88:89]
	v_pk_add_f32 v[86:87], v[86:87], v[130:131]
	v_pk_mul_f32 v[84:85], v[92:93], v[84:85]
	v_pk_add_f32 v[82:83], v[82:83], v[130:131]
	v_pk_mul_f32 v[80:81], v[92:93], v[80:81]
	v_pk_add_f32 v[78:79], v[78:79], v[130:131]
	v_pk_mul_f32 v[76:77], v[92:93], v[76:77]
	v_pk_add_f32 v[74:75], v[74:75], v[130:131]
	v_pk_mul_f32 v[72:73], v[92:93], v[72:73]
	v_pk_add_f32 v[70:71], v[70:71], v[130:131]
	v_pk_mul_f32 v[68:69], v[92:93], v[68:69]
	v_pk_add_f32 v[62:63], v[62:63], v[130:131]
	v_pk_mul_f32 v[60:61], v[92:93], v[60:61]
	v_pk_mul_f32 v[98:99], v[94:95], v[98:99]
	v_cvt_pk_bf16_f32 v96, v96, v97
	v_pk_mul_f32 v[90:91], v[94:95], v[90:91]
	v_cvt_pk_bf16_f32 v97, v98, v99
	global_store_dwordx2 v[124:125], v[96:97], off offset:32
	v_cvt_pk_bf16_f32 v88, v88, v89
	v_cvt_pk_bf16_f32 v89, v90, v91
	global_store_dwordx2 v[120:121], v[88:89], off offset:32
	v_pk_mul_f32 v[86:87], v[94:95], v[86:87]
	v_cvt_pk_bf16_f32 v84, v84, v85
	v_pk_mul_f32 v[82:83], v[94:95], v[82:83]
	v_cvt_pk_bf16_f32 v85, v86, v87
	global_store_dwordx2 v[116:117], v[84:85], off offset:32
	v_cvt_pk_bf16_f32 v80, v80, v81
	v_cvt_pk_bf16_f32 v81, v82, v83
	global_store_dwordx2 v[112:113], v[80:81], off offset:32
	v_pk_mul_f32 v[78:79], v[94:95], v[78:79]
	v_cvt_pk_bf16_f32 v76, v76, v77
	v_pk_mul_f32 v[74:75], v[94:95], v[74:75]
	v_cvt_pk_bf16_f32 v77, v78, v79
	global_store_dwordx2 v[106:107], v[76:77], off offset:32
	v_cvt_pk_bf16_f32 v72, v72, v73
	v_cvt_pk_bf16_f32 v73, v74, v75
	global_store_dwordx2 v[104:105], v[72:73], off offset:32
	v_pk_mul_f32 v[70:71], v[94:95], v[70:71]
	v_cvt_pk_bf16_f32 v68, v68, v69
	v_pk_mul_f32 v[62:63], v[94:95], v[62:63]
	v_cvt_pk_bf16_f32 v69, v70, v71
	global_store_dwordx2 v[102:103], v[68:69], off offset:32
	v_cvt_pk_bf16_f32 v60, v60, v61
	v_cvt_pk_bf16_f32 v61, v62, v63
	global_store_dwordx2 v[100:101], v[60:61], off offset:32
	s_nop 0
	v_mov_b32_e32 v68, v162
	v_mov_b32_e32 v69, v163
	v_mov_b32_e32 v70, v164
	v_mov_b32_e32 v71, v165
	v_mov_b32_e32 v60, 0
	s_and_b64 vcc, exec, s[4:5]
	v_mov_b32_e32 v72, 0
	v_mov_b32_e32 v73, 0
	v_mov_b32_e32 v74, 0
	v_mov_b32_e32 v75, 0
	s_cbranch_vccnz .LBB0_273
	v_mov_b32_e32 v72, v174
	v_mov_b32_e32 v73, v175
	v_mov_b32_e32 v74, v176
	v_mov_b32_e32 v75, v177
; __device__ __forceinline__ unsigned cvt_pk_bf16(float lo, float hi) { unsigned r; asm volatile("s_nop 0\n\tv_cvt_pk_bf16_f32 %0, %1, %2\n\ts_nop 1" : "=v"(r) : "v"(lo), "v"(hi)); return r; }
;     __device__ __forceinline__ void operator()(f32x4 (&acc)[2][2][4][2], const Unit& u, int wr, int wc, int fr, int fq) const {
;     ...
;         for (int bj = 0; bj < 2; ++bj)
; #pragma unroll
;             for (int n = 0; n < 2; ++n) { const int col = col0 + bj * 128 + n * 16; const f32x4 gv = *(const f32x4*)(gr + col);
;                 f32x4 bv = (f32x4){0.f, 0.f, 0.f, 0.f}; if (bias) bv = *(const f32x4*)(bias + col);
; #pragma unroll
;                 for (int ai = 0; ai < 2; ++ai)
; #pragma unroll
;                     for (int m = 0; m < 4; ++m) { const size_t row = row0 + ai * 128 + m * 16;
;                         const f32x4 o = gv * (acc[ai][bj][m][n] + bv); u32x2 w; w.x = cvt_pk_bf16(o[0], o[1]); w.y = cvt_pk_bf16(o[2], o[3]);
;                         *(u32x2*)(O + row * 1024 + col) = w; } }
.LBB0_273:
	v_pk_add_f32 v[64:65], v[64:65], v[72:73]
	v_pk_add_f32 v[56:57], v[56:57], v[72:73]
	v_pk_add_f32 v[52:53], v[52:53], v[72:73]
	v_pk_add_f32 v[48:49], v[48:49], v[72:73]
	v_pk_add_f32 v[44:45], v[44:45], v[72:73]
	v_pk_add_f32 v[40:41], v[40:41], v[72:73]
	v_pk_add_f32 v[32:33], v[32:33], v[72:73]
	v_pk_add_f32 v[24:25], v[24:25], v[72:73]
	v_pk_add_f32 v[62:63], v[66:67], v[74:75]
	v_pk_mul_f32 v[64:65], v[68:69], v[64:65]
	v_pk_add_f32 v[58:59], v[58:59], v[74:75]
	v_pk_mul_f32 v[56:57], v[68:69], v[56:57]
	v_pk_add_f32 v[54:55], v[54:55], v[74:75]
	v_pk_mul_f32 v[52:53], v[68:69], v[52:53]
	v_pk_add_f32 v[50:51], v[50:51], v[74:75]
	v_pk_mul_f32 v[48:49], v[68:69], v[48:49]
	v_pk_add_f32 v[46:47], v[46:47], v[74:75]
	v_pk_mul_f32 v[44:45], v[68:69], v[44:45]
	v_pk_add_f32 v[42:43], v[42:43], v[74:75]
	v_pk_mul_f32 v[40:41], v[68:69], v[40:41]
	v_pk_add_f32 v[34:35], v[34:35], v[74:75]
	v_pk_mul_f32 v[32:33], v[68:69], v[32:33]
	v_pk_add_f32 v[26:27], v[26:27], v[74:75]
	v_pk_mul_f32 v[24:25], v[68:69], v[24:25]
	v_pk_mul_f32 v[62:63], v[70:71], v[62:63]
	v_cvt_pk_bf16_f32 v64, v64, v65
	v_pk_mul_f32 v[58:59], v[70:71], v[58:59]
	v_cvt_pk_bf16_f32 v65, v62, v63
	global_store_dwordx2 v[124:125], v[64:65], off offset:256
	v_cvt_pk_bf16_f32 v56, v56, v57
	v_cvt_pk_bf16_f32 v57, v58, v59
	global_store_dwordx2 v[120:121], v[56:57], off offset:256
	v_pk_mul_f32 v[54:55], v[70:71], v[54:55]
	v_cvt_pk_bf16_f32 v52, v52, v53
	v_pk_mul_f32 v[50:51], v[70:71], v[50:51]
	v_cvt_pk_bf16_f32 v53, v54, v55
	global_store_dwordx2 v[116:117], v[52:53], off offset:256
	v_cvt_pk_bf16_f32 v48, v48, v49
	v_cvt_pk_bf16_f32 v49, v50, v51
	global_store_dwordx2 v[112:113], v[48:49], off offset:256
	v_pk_mul_f32 v[46:47], v[70:71], v[46:47]
	v_cvt_pk_bf16_f32 v44, v44, v45
	v_pk_mul_f32 v[42:43], v[70:71], v[42:43]
	v_cvt_pk_bf16_f32 v45, v46, v47
	global_store_dwordx2 v[106:107], v[44:45], off offset:256
	v_cvt_pk_bf16_f32 v40, v40, v41
	v_cvt_pk_bf16_f32 v41, v42, v43
	global_store_dwordx2 v[104:105], v[40:41], off offset:256
	v_pk_mul_f32 v[34:35], v[70:71], v[34:35]
	v_cvt_pk_bf16_f32 v32, v32, v33
	v_pk_mul_f32 v[26:27], v[70:71], v[26:27]
	v_cvt_pk_bf16_f32 v33, v34, v35
	global_store_dwordx2 v[102:103], v[32:33], off offset:256
	v_cvt_pk_bf16_f32 v24, v24, v25
	v_cvt_pk_bf16_f32 v25, v26, v27
	global_store_dwordx2 v[100:101], v[24:25], off offset:256
	s_nop 0
	v_mov_b32_e32 v24, v166
	v_mov_b32_e32 v25, v167
	v_mov_b32_e32 v26, v168
	v_mov_b32_e32 v27, v169
	s_and_b64 vcc, exec, s[4:5]
	v_mov_b32_e32 v61, 0
	v_mov_b32_e32 v62, 0
	v_mov_b32_e32 v63, 0
	s_cbranch_vccnz .LBB0_258
	v_mov_b32_e32 v60, v178
	v_mov_b32_e32 v61, v179
	v_mov_b32_e32 v62, v180
	v_mov_b32_e32 v63, v181
	s_branch .LBB0_258

; __device__ __forceinline__ unsigned cvt_pk_bf16(float lo, float hi) { unsigned r; asm volatile("s_nop 0\n\tv_cvt_pk_bf16_f32 %0, %1, %2\n\ts_nop 1" : "=v"(r) : "v"(lo), "v"(hi)); return r; }
; #define LAS __attribute__((address_space(3)))
; __device__ __forceinline__ f32x16 mfma32(bf16x8 a, bf16x8 b, f32x16 c) { return __builtin_amdgcn_mfma_f32_32x32x16_bf16(a, b, c, 0, 0, 0); }
;     ...
;             for (int bidx = wid; bidx < 10; bidx += 8) {
;                 int bi2 = bidx >= 6 ? 3 : bidx >= 3 ? 2 : bidx >= 1 ? 1 : 0; int bj2 = bidx - bi2 * (bi2 + 1) / 2;
;                 const int ibk = DIR ? 3 - bi2 : bi2, jbk = DIR ? 3 - bj2 : bj2;
;                 const unsigned io2 = rowoff + (unsigned)ibk * 8192u, jo2 = rowoff + (unsigned)jbk * 8192u;
;                 f32x16 S;
; #pragma unroll
;                 for (int e = 0; e < 16; ++e) S[e] = 0.f;
; #pragma unroll
;                 for (int s8 = 0; s8 < 8; ++s8) S = mfma32(t_ld8(TB, jo2, rx4, 2 * s8 + h), t_ld8(TA, io2, rx4, 2 * s8 + h), S);
;                 asm volatile("s_nop 15\n\ts_nop 3" : "+v"(S));
;                 LAS u32x4* dstp = (LAS u32x4*)(CBL + bidx * 2048 + lane * 32);
;                 u32x4 w0, w1; w0.x = cvt_pk_bf16(S[0], S[1]); w0.y = cvt_pk_bf16(S[2], S[3]); w0.z = cvt_pk_bf16(S[4], S[5]); w0.w = cvt_pk_bf16(S[6], S[7]);
;                 w1.x = cvt_pk_bf16(S[8], S[9]); w1.y = cvt_pk_bf16(S[10], S[11]); w1.z = cvt_pk_bf16(S[12], S[13]); w1.w = cvt_pk_bf16(S[14], S[15]);
;                 dstp[0] = w0; dstp[1] = w1;
;             }
.LBB0_429:
	s_cmp_gt_i32 s63, 0
	s_cselect_b64 s[84:85], -1, 0
	s_nop 5
	v_cndmask_b32_e64 v64, 0, 1, s[84:85]
	s_cmp_lt_i32 s63, 3
	v_readfirstlane_b32 s66, v64
	s_cselect_b32 s66, s66, 2
	s_cmp_lt_i32 s63, 6
	s_cselect_b32 s66, s66, 3
	s_add_i32 s69, s66, 1
	s_mul_i32 s69, s69, s66
	s_lshr_b32 s69, s69, 1
	s_lshl_b32 s66, s66, 13
	v_mov_b32_e32 v64, 0x6000
	v_bitop3_b32 v64, s66, v64, v103 bitop3:0x36
	s_add_i32 s66, s62, s69
	v_lshl_add_u32 v81, s66, 13, v163
	v_add_u32_e32 v82, 0, v64
	v_add_u32_e32 v64, v81, v115
	v_add_u32_e32 v68, v82, v115
	ds_read_b128 v[64:67], v64 offset:57344
	ds_read_b128 v[68:71], v68
	v_add_u32_e32 v136, v81, v166
	v_add_u32_e32 v144, v82, v166
	ds_read_b128 v[136:139], v136 offset:57344
	ds_read_b128 v[144:147], v144
	v_add_u32_e32 v148, v81, v167
	v_add_u32_e32 v154, v82, v167
	ds_read_b128 v[148:151], v148 offset:57344
	ds_read_b128 v[154:157], v154
	s_add_i32 s66, s63, 8
	s_add_i32 s62, s62, -8
	s_cmp_gt_i32 s63, 1
	s_mov_b32 s63, s66
	v_add_u32_e32 v216, v81, v168
	v_add_u32_e32 v220, v82, v168
	ds_read_b128 v[216:219], v216 offset:57344
	ds_read_b128 v[220:223], v220
	s_waitcnt lgkmcnt(6)
	v_mfma_f32_32x32x16_bf16 v[64:79], v[64:67], v[68:71], 0
	v_add_u32_e32 v224, v81, v169
	v_add_u32_e32 v248, v82, v169
	ds_read_b128 v[224:227], v224 offset:57344
	ds_read_b128 v[248:251], v248
	s_waitcnt lgkmcnt(6)
	v_mfma_f32_32x32x16_bf16 v[64:79], v[136:139], v[144:147], v[64:79]
	v_add_u32_e32 v136, v81, v170
	v_add_u32_e32 v144, v82, v170
	ds_read_b128 v[136:139], v136 offset:57344
	ds_read_b128 v[144:147], v144
	s_waitcnt lgkmcnt(6)
	v_mfma_f32_32x32x16_bf16 v[64:79], v[148:151], v[154:157], v[64:79]
	v_add_u32_e32 v148, v81, v171
	v_add_u32_e32 v154, v82, v171
	ds_read_b128 v[148:151], v148 offset:57344
	ds_read_b128 v[154:157], v154
	s_waitcnt lgkmcnt(6)
	v_mfma_f32_32x32x16_bf16 v[64:79], v[216:219], v[220:223], v[64:79]
	v_add_u32_e32 v216, v81, v172
	v_add_u32_e32 v220, v82, v172
	ds_read_b128 v[216:219], v216 offset:57344
	ds_read_b128 v[220:223], v220
	s_waitcnt lgkmcnt(6)
	v_mfma_f32_32x32x16_bf16 v[64:79], v[224:227], v[248:251], v[64:79]
	s_waitcnt lgkmcnt(4)
	v_mfma_f32_32x32x16_bf16 v[64:79], v[136:139], v[144:147], v[64:79]
	s_waitcnt lgkmcnt(2)
	v_mfma_f32_32x32x16_bf16 v[64:79], v[148:151], v[154:157], v[64:79]
	s_waitcnt lgkmcnt(0)
	v_mfma_f32_32x32x16_bf16 v[64:79], v[216:219], v[220:223], v[64:79]
	v_add_u32_e32 v81, -16, v80
	s_nop 15
	s_nop 3
	s_nop 0
	s_nop 0
	v_cvt_pk_bf16_f32 v64, v64, v65
	s_nop 0
	v_cvt_pk_bf16_f32 v65, v66, v67
	s_nop 0
	v_cvt_pk_bf16_f32 v66, v68, v69
	s_nop 0
	v_cvt_pk_bf16_f32 v67, v70, v71
	s_nop 0
	v_cvt_pk_bf16_f32 v68, v72, v73
	s_nop 0
	v_cvt_pk_bf16_f32 v69, v74, v75
	s_nop 0
	v_cvt_pk_bf16_f32 v70, v76, v77
	s_nop 0
	v_cvt_pk_bf16_f32 v71, v78, v79
	s_nop 10
	ds_write_b128 v81, v[64:67]
	ds_write_b128 v80, v[68:71]
	v_add_u32_e32 v80, 0x4000, v80
	s_cbranch_scc0 .LBB0_429

; __device__ __forceinline__ unsigned cvt_pk_bf16(float lo, float hi) { unsigned r; asm volatile("s_nop 0\n\tv_cvt_pk_bf16_f32 %0, %1, %2\n\ts_nop 1" : "=v"(r) : "v"(lo), "v"(hi)); return r; }
; #define LAS __attribute__((address_space(3)))
; __device__ __forceinline__ f32x16 mfma32(bf16x8 a, bf16x8 b, f32x16 c) { return __builtin_amdgcn_mfma_f32_32x32x16_bf16(a, b, c, 0, 0, 0); }
;     ...
;             for (int bidx = wid; bidx < 10; bidx += 8) {
;                 int bi2 = bidx >= 6 ? 3 : bidx >= 3 ? 2 : bidx >= 1 ? 1 : 0; int bj2 = bidx - bi2 * (bi2 + 1) / 2;
;                 const int ibk = DIR ? 3 - bi2 : bi2, jbk = DIR ? 3 - bj2 : bj2;
;                 const unsigned io2 = rowoff + (unsigned)ibk * 8192u, jo2 = rowoff + (unsigned)jbk * 8192u;
;                 f32x16 S;
; #pragma unroll
;                 for (int e = 0; e < 16; ++e) S[e] = 0.f;
; #pragma unroll
;                 for (int s8 = 0; s8 < 8; ++s8) S = mfma32(t_ld8(TB, jo2, rx4, 2 * s8 + h), t_ld8(TA, io2, rx4, 2 * s8 + h), S);
;                 asm volatile("s_nop 15\n\ts_nop 3" : "+v"(S));
;                 LAS u32x4* dstp = (LAS u32x4*)(CBL + bidx * 2048 + lane * 32);
;                 u32x4 w0, w1; w0.x = cvt_pk_bf16(S[0], S[1]); w0.y = cvt_pk_bf16(S[2], S[3]); w0.z = cvt_pk_bf16(S[4], S[5]); w0.w = cvt_pk_bf16(S[6], S[7]);
;                 w1.x = cvt_pk_bf16(S[8], S[9]); w1.y = cvt_pk_bf16(S[10], S[11]); w1.z = cvt_pk_bf16(S[12], S[13]); w1.w = cvt_pk_bf16(S[14], S[15]);
;                 dstp[0] = w0; dstp[1] = w1;
;             }
.LBB0_451:
	s_cmp_gt_i32 s33, 0
	s_cselect_b64 s[58:59], -1, 0
	s_nop 2
	v_cndmask_b32_e64 v64, 0, 1, s[58:59]
	s_cmp_lt_i32 s33, 3
	v_readfirstlane_b32 s55, v64
	s_cselect_b32 s55, s55, 2
	s_cmp_lt_i32 s33, 6
	s_cselect_b32 s55, s55, 3
	s_add_i32 s58, s55, 1
	s_mul_i32 s58, s58, s55
	v_lshl_add_u32 v94, s55, 13, v163
	s_lshl_b32 s55, s58, 12
	s_and_b32 s55, s55, 0x1e000
	s_sub_i32 s55, 0, s55
	v_add_u32_e32 v64, s55, v81
	v_add_u32_e32 v68, v94, v115
	ds_read_b128 v[64:67], v64
	ds_read_b128 v[68:71], v68
	v_add_u32_e32 v81, 0x10000, v81
	v_add_u32_e32 v90, s55, v82
	v_add_u32_e32 v150, v94, v166
	ds_read_b128 v[90:93], v90
	ds_read_b128 v[150:153], v150
	v_add_u32_e32 v82, 0x10000, v82
	v_add_u32_e32 v220, s55, v83
	v_add_u32_e32 v224, v94, v167
	ds_read_b128 v[220:223], v220
	ds_read_b128 v[224:227], v224
	v_add_u32_e32 v83, 0x10000, v83
	v_add_u32_e32 v228, s55, v84
	v_add_u32_e32 v246, v94, v168
	ds_read_b128 v[228:231], v228
	ds_read_b128 v[246:249], v246
	v_add_u32_e32 v84, 0x10000, v84
	s_waitcnt lgkmcnt(6)
	v_mfma_f32_32x32x16_bf16 v[64:79], v[64:67], v[68:71], 0
	v_add_u32_e32 v128, s55, v85
	v_add_u32_e32 v194, v94, v169
	ds_read_b128 v[128:131], v128
	ds_read_b128 v[194:197], v194
	v_add_u32_e32 v85, 0x10000, v85
	s_waitcnt lgkmcnt(6)
	v_mfma_f32_32x32x16_bf16 v[64:79], v[90:93], v[150:153], v[64:79]
	v_add_u32_e32 v90, s55, v86
	v_add_u32_e32 v150, v94, v170
	ds_read_b128 v[90:93], v90
	ds_read_b128 v[150:153], v150
	v_add_u32_e32 v86, 0x10000, v86
	s_waitcnt lgkmcnt(6)
	v_mfma_f32_32x32x16_bf16 v[64:79], v[220:223], v[224:227], v[64:79]
	v_add_u32_e32 v220, s55, v87
	v_add_u32_e32 v224, v94, v171
	ds_read_b128 v[220:223], v220
	ds_read_b128 v[224:227], v224
	v_add_u32_e32 v87, 0x10000, v87
	s_waitcnt lgkmcnt(6)
	v_mfma_f32_32x32x16_bf16 v[64:79], v[228:231], v[246:249], v[64:79]
	v_add_u32_e32 v228, s55, v88
	v_add_u32_e32 v246, v94, v172
	ds_read_b128 v[228:231], v228
	ds_read_b128 v[246:249], v246
	v_add_u32_e32 v88, 0x10000, v88
	s_waitcnt lgkmcnt(6)
	v_mfma_f32_32x32x16_bf16 v[64:79], v[128:131], v[194:197], v[64:79]
	s_waitcnt lgkmcnt(4)
	v_mfma_f32_32x32x16_bf16 v[64:79], v[90:93], v[150:153], v[64:79]
	s_waitcnt lgkmcnt(2)
	v_mfma_f32_32x32x16_bf16 v[64:79], v[220:223], v[224:227], v[64:79]
	s_waitcnt lgkmcnt(0)
	v_mfma_f32_32x32x16_bf16 v[64:79], v[228:231], v[246:249], v[64:79]
	s_add_i32 s55, s33, 8
	s_cmp_gt_i32 s33, 1
	s_mov_b32 s33, s55
	s_nop 15
	s_nop 3
	v_add_u32_e32 v90, 0, v89
	v_add_u32_e32 v91, 0x20000, v90
	s_nop 0
	v_cvt_pk_bf16_f32 v64, v64, v65
	s_nop 0
	v_cvt_pk_bf16_f32 v65, v66, v67
	s_nop 0
	v_cvt_pk_bf16_f32 v66, v68, v69
	s_nop 0
	v_cvt_pk_bf16_f32 v67, v70, v71
	s_nop 0
	v_cvt_pk_bf16_f32 v68, v72, v73
	s_nop 0
	v_cvt_pk_bf16_f32 v69, v74, v75
	s_nop 0
	v_cvt_pk_bf16_f32 v70, v76, v77
	s_nop 0
	v_cvt_pk_bf16_f32 v71, v78, v79
	s_nop 9
	ds_write_b128 v91, v[64:67]
	v_add_u32_e32 v64, 0x20010, v90
	v_add_u32_e32 v89, 0x4000, v89
	ds_write_b128 v64, v[68:71]
	s_cbranch_scc0 .LBB0_451
